# wave priority 1 inside the in-proj (A) and out-proj (D1) GEMM k-loops (priority 2 kept in the phase-B tile loop)
# speedup vs baseline: 1.0916x; 1.0051x over previous
; DI char* opq(char* q) { size_t z = 0; asm volatile("" : "+s"(z)); return q + z; }
; DI int tidx() { int t = threadIdx.x; asm volatile("" : "+v"(t)); return t; }
; #define GLOAD(dst, kt_) _Pragma("unroll") for (int i = 0; i < NCH; ++i) { dst[i] = (i < NCHW) ? ldw(i, tid >> 3, (kt_) * 64 + (tid & 7) * 8) : ldx(i - NCHW, tid >> 3, (kt_) * 64 + (tid & 7) * 8); }
; #define LSTORE(src, base) _Pragma("unroll") for (int i = 0; i < NCH; ++i) { const int c = tid + 256 * i; *(u32x4*)((base) + (c >> 3) * 144 + (c & 7) * 16) = src[i]; }
; template <int WGN, int INS, int IMS, bool DB, class LdW, class LdX>
; DI void gemm_core(f32x16 (&acc)[INS][IMS], const int KT, LdW ldw, LdX ldx, char* lds, const int tid) {
;   constexpr int WGM = 4 / WGN;
;   constexpr int WROWS = WGN * 32 * INS, XROWS = WGM * 32 * IMS, NROWS = WROWS + XROWS, NCH = NROWS / 32, NCHW = WROWS / 32, BUFB = NROWS * 144;
;   const int lane = tid & 63, wid = tid >> 6, l31 = lane & 31, hi = lane >> 5;
;   const int wn = (WGN == 2) ? (wid >> 1) : wid, wm = (WGN == 2) ? (wid & 1) : 0;
;   const int offa = (wn * 32 * INS + l31) * 144 + hi * 16;
;   const int offb = (WROWS + wm * 32 * IMS + l31) * 144 + hi * 16;
; #pragma unroll
;   for (int a = 0; a < INS; ++a)
; #pragma unroll
;     for (int b = 0; b < IMS; ++b)
; #pragma unroll
;       for (int r = 0; r < 16; ++r) acc[a][b][r] = 0.f;
;     ...
;   if (DB) {
;     u32x4 preA[NCH], preB[NCH];
;     GLOAD(preA, 0)
;     GLOAD(preB, 1)
;     __syncthreads();
;     LSTORE(preA, lds)
;     __syncthreads();
; template <int NTW>
; DI void inproj_tile(const Params& p, int l, int mt, int ntile, char* lds) {
;   char* const ws_ = opq(p.ws);
;   const u16* W = (const u16*)(ws_ + OFF_WIN) + ((size_t)l * NP + ntile * 64 * NTW) * 1024;
;   const u16* X = (const u16*)(ws_ + OFF_XB) + (size_t)mt * 128 * 1024;
;   f32x16 acc[NTW][2];
;   const int tid = tidx();
;   gemm_core<2, NTW, 2, (NTW == 2)>(acc, 16, [&](int i, int r0, int k) -> u32x4 { return *(const u32x4*)((W + i * 32768) + (unsigned)(r0 * 1024 + k)); },
;                [&](int i, int r0, int k) -> u32x4 { return *(const u32x4*)((X + i * 32768) + (unsigned)(r0 * 1024 + k)); }, lds, tid);
.LBB0_163:
	s_lshl_b32 s0, s26, 4
	s_and_b32 s0, s0, 0x70
	s_bfe_u32 s1, s26, 0x40003
	s_or_b32 s4, s0, s1
	s_mov_b64 s[0:1], 0
	s_add_u32 s27, s90, s0
	s_addc_u32 s28, s91, s1
	s_lshl_b32 s0, s26, 1
	s_and_b32 s0, s0, 0xffffff00
	v_readlane_b32 s2, v234, 24
	s_ashr_i32 s1, s0, 31
	s_mulk_i32 s2, 0xd00
	s_add_u32 s2, s0, s2
	s_addc_u32 s3, s1, 0
	s_lshl_b64 s[2:3], s[2:3], 11
	s_add_u32 s2, s27, s2
	s_addc_u32 s3, s28, s3
	s_lshl_b32 s80, s4, 7
	s_lshl_b32 s4, s4, 18
	s_add_u32 s24, s27, s4
	s_addc_u32 s25, s28, 0
	s_add_u32 s4, s24, 0x2a40000
	s_addc_u32 s5, s25, 0
	v_mov_b32_e32 v181, v176
	v_and_b32_e32 v183, 0x5f, v181
	v_lshrrev_b32_e32 v185, 3, v181
	v_or_b32_e32 v254, s80, v183
	v_lshlrev_b32_e32 v254, 2, v254
	s_add_u32 s14, s27, 0x4a40000
	s_addc_u32 s15, s28, 0
	global_load_dword v252, v254, s[14:15] sc1
	global_load_dword v253, v254, s[14:15] offset:128 sc1
	v_and_b32_e32 v220, 63, v181
	v_lshrrev_b32_e32 v221, 6, v181
	v_lshrrev_b32_e32 v222, 3, v220
	v_readfirstlane_b32 s13, v221
	v_and_b32_e32 v223, 7, v220
	v_bfe_u32 v224, v220, 4, 2
	v_xor_b32_e32 v223, v223, v224
	v_lshlrev_b32_e32 v223, 4, v223
	v_and_b32_e32 v224, 1, v221
	v_lshrrev_b32_e32 v225, 1, v221
	v_lshlrev_b32_e32 v224, 5, v224
	v_lshl_add_u32 v224, v225, 7, v224
	v_add_u32_e32 v224, v224, v222
	v_lshl_add_u32 v225, v221, 5, v222
	v_lshl_or_b32 v210, v224, 11, v223
	v_lshl_or_b32 v216, v225, 11, v223
	v_xor_b32_e32 v224, 64, v210
	v_xor_b32_e32 v225, 64, v216
	v_add_u32_e32 v211, 0x3c00, v224
	v_add_u32_e32 v217, 0x3c00, v225
	v_add_u32_e32 v212, 0x7800, v210
	v_add_u32_e32 v218, 0x7800, v216
	v_add_u32_e32 v213, 0xb400, v224
	v_add_u32_e32 v219, 0xb400, v225
	v_and_b32_e32 v222, 31, v220
	v_lshrrev_b32_e32 v223, 5, v220
	v_bfe_u32 v224, v220, 1, 3
	v_xor_b32_e32 v223, v223, v224
	v_lshlrev_b32_e32 v223, 4, v223
	v_lshrrev_b32_e32 v224, 1, v221
	v_and_b32_e32 v225, 1, v221
	v_lshl_add_u32 v224, v224, 6, v222
	v_lshl_add_u32 v225, v225, 6, v222
	v_lshl_or_b32 v202, v224, 7, v223
	v_lshl_or_b32 v206, v225, 7, v223
	v_xor_b32_e32 v203, 32, v202
	v_xor_b32_e32 v207, 32, v206
	v_xor_b32_e32 v204, 64, v202
	v_xor_b32_e32 v208, 64, v206
	v_xor_b32_e32 v205, 96, v202
	v_xor_b32_e32 v209, 96, v206
	s_lshl_b32 s13, s13, 12
	s_sub_u32 s10, s4, 0x80
	s_subb_u32 s11, s5, 0
	s_add_u32 s8, s2, 0x1ff80
	s_addc_u32 s9, s3, 0
	s_sub_u32 s6, s2, 0x80
	s_subb_u32 s7, s3, 0
	s_mov_b32 s12, 0
	s_setprio 1
	s_waitcnt lgkmcnt(0)
	s_barrier
	s_add_u32 s10, s10, 0x80
	s_addc_u32 s11, s11, 0
	s_add_u32 m0, s13, 0
	s_nop 0
	global_load_lds_dwordx4 v216, s[10:11] sc1
	global_load_lds_dwordx4 v217, s[10:11] offset:1024 sc1
	global_load_lds_dwordx4 v218, s[10:11] offset:2048 sc1
	global_load_lds_dwordx4 v219, s[10:11] offset:3072 sc1
	s_add_u32 s6, s6, 0x80
	s_addc_u32 s7, s7, 0
	s_add_u32 m0, s13, 32768
	s_nop 0
	global_load_lds_dwordx4 v210, s[6:7]
	global_load_lds_dwordx4 v211, s[6:7] offset:1024
	global_load_lds_dwordx4 v212, s[6:7] offset:2048
	global_load_lds_dwordx4 v213, s[6:7] offset:3072
	v_mov_b32_e32 v112, 0
	v_mov_b32_e32 v113, 0
	v_mov_b32_e32 v114, 0
	v_mov_b32_e32 v115, 0
	v_mov_b32_e32 v116, 0
	v_mov_b32_e32 v117, 0
	v_mov_b32_e32 v118, 0
	v_mov_b32_e32 v119, 0
	v_mov_b32_e32 v120, 0
	v_mov_b32_e32 v121, 0
	v_mov_b32_e32 v122, 0
	v_mov_b32_e32 v123, 0
	v_mov_b32_e32 v124, 0
	v_mov_b32_e32 v125, 0
	v_mov_b32_e32 v126, 0
	v_mov_b32_e32 v127, 0
	v_mov_b32_e32 v48, 0
	v_mov_b32_e32 v49, 0
	v_mov_b32_e32 v50, 0
	v_mov_b32_e32 v51, 0
	v_mov_b32_e32 v52, 0
	v_mov_b32_e32 v53, 0
	v_mov_b32_e32 v54, 0
	v_mov_b32_e32 v55, 0
	v_mov_b32_e32 v56, 0
	v_mov_b32_e32 v57, 0
	v_mov_b32_e32 v58, 0
	v_mov_b32_e32 v59, 0
	v_mov_b32_e32 v60, 0
	v_mov_b32_e32 v61, 0
	v_mov_b32_e32 v62, 0
	v_mov_b32_e32 v63, 0
	v_mov_b32_e32 v96, 0
	v_mov_b32_e32 v97, 0
	v_mov_b32_e32 v98, 0
	v_mov_b32_e32 v99, 0
	v_mov_b32_e32 v100, 0
	v_mov_b32_e32 v101, 0
	v_mov_b32_e32 v102, 0
	v_mov_b32_e32 v103, 0
	v_mov_b32_e32 v104, 0
	v_mov_b32_e32 v105, 0
	v_mov_b32_e32 v106, 0
	v_mov_b32_e32 v107, 0
	v_mov_b32_e32 v108, 0
	v_mov_b32_e32 v109, 0
	v_mov_b32_e32 v110, 0
	v_mov_b32_e32 v111, 0
	v_mov_b32_e32 v32, 0
	v_mov_b32_e32 v33, 0
	v_mov_b32_e32 v34, 0
	v_mov_b32_e32 v35, 0
	v_mov_b32_e32 v36, 0
	v_mov_b32_e32 v37, 0
	v_mov_b32_e32 v38, 0
	v_mov_b32_e32 v39, 0
	v_mov_b32_e32 v40, 0
	v_mov_b32_e32 v41, 0
	v_mov_b32_e32 v42, 0
	v_mov_b32_e32 v43, 0
	v_mov_b32_e32 v44, 0
	v_mov_b32_e32 v45, 0
	v_mov_b32_e32 v46, 0
	v_mov_b32_e32 v47, 0
	v_mov_b32_e32 v80, 0
	v_mov_b32_e32 v81, 0
	v_mov_b32_e32 v82, 0
	v_mov_b32_e32 v83, 0
	v_mov_b32_e32 v84, 0
	v_mov_b32_e32 v85, 0
	v_mov_b32_e32 v86, 0
	v_mov_b32_e32 v87, 0
	v_mov_b32_e32 v88, 0
	v_mov_b32_e32 v89, 0
	v_mov_b32_e32 v90, 0
	v_mov_b32_e32 v91, 0
	v_mov_b32_e32 v92, 0
	v_mov_b32_e32 v93, 0
	v_mov_b32_e32 v94, 0
	v_mov_b32_e32 v95, 0
	v_mov_b32_e32 v16, 0
	v_mov_b32_e32 v17, 0
	v_mov_b32_e32 v18, 0
	v_mov_b32_e32 v19, 0
	v_mov_b32_e32 v20, 0
	v_mov_b32_e32 v21, 0
	v_mov_b32_e32 v22, 0
	v_mov_b32_e32 v23, 0
	v_mov_b32_e32 v24, 0
	v_mov_b32_e32 v25, 0
	v_mov_b32_e32 v26, 0
	v_mov_b32_e32 v27, 0
	v_mov_b32_e32 v28, 0
	v_mov_b32_e32 v29, 0
	v_mov_b32_e32 v30, 0
	v_mov_b32_e32 v31, 0
	v_mov_b32_e32 v64, 0
	v_mov_b32_e32 v65, 0
	v_mov_b32_e32 v66, 0
	v_mov_b32_e32 v67, 0
	v_mov_b32_e32 v68, 0
	v_mov_b32_e32 v69, 0
	v_mov_b32_e32 v70, 0
	v_mov_b32_e32 v71, 0
	v_mov_b32_e32 v72, 0
	v_mov_b32_e32 v73, 0
	v_mov_b32_e32 v74, 0
	v_mov_b32_e32 v75, 0
	v_mov_b32_e32 v76, 0
	v_mov_b32_e32 v77, 0
	v_mov_b32_e32 v78, 0
	v_mov_b32_e32 v79, 0
	v_mov_b32_e32 v0, 0
	v_mov_b32_e32 v1, 0
	v_mov_b32_e32 v2, 0
	v_mov_b32_e32 v3, 0
	v_mov_b32_e32 v4, 0
	v_mov_b32_e32 v5, 0
	v_mov_b32_e32 v6, 0
	v_mov_b32_e32 v7, 0
	v_mov_b32_e32 v8, 0
	v_mov_b32_e32 v9, 0
	v_mov_b32_e32 v10, 0
	v_mov_b32_e32 v11, 0
	v_mov_b32_e32 v12, 0
	v_mov_b32_e32 v13, 0
	v_mov_b32_e32 v14, 0
	v_mov_b32_e32 v15, 0

; template <int NTW>
; DI void inproj_tile(const Params& p, int l, int mt, int ntile, char* lds) {
;     ...
;   const int lane = tid & 63, wid = tid >> 6, l31 = lane & 31, hi = lane >> 5, wn = wid >> 1, wm = wid & 1;
;   const float* rn = (const float*)(ws_ + OFF_RN);
;   u16* proj = (u16*)(ws_ + OFF_PROJ);
;   constexpr int NCOLS = 64 * NTW, RS = NCOLS * 2 + 16;
;   __syncthreads();
; #pragma unroll
;   for (int im = 0; im < 2; ++im) {
;     const int tl = wm * 64 + im * 32 + l31;
;     const float r = rn[(size_t)mt * 128 + tl];
; #pragma unroll
;     for (int in = 0; in < NTW; ++in)
; #pragma unroll
;       for (int g = 0; g < 4; ++g) {
;         const int n = wn * 32 * NTW + in * 32 + 8 * g + 4 * hi;
;         u32x2 o; o[0] = pk2(acc[in][im][4 * g] * r, acc[in][im][4 * g + 1] * r); o[1] = pk2(acc[in][im][4 * g + 2] * r, acc[in][im][4 * g + 3] * r);
;         *(u32x2*)(lds + tl * RS + n * 2) = o;
;       }
;   }
;   __syncthreads();
.Lga_p1c:
	s_waitcnt lgkmcnt(6)
	v_mfma_f32_32x32x16_bf16 v[80:95], v[128:131], v[160:163], v[80:95]
	v_mfma_f32_32x32x16_bf16 v[16:31], v[128:131], v[236:239], v[16:31]
	v_mfma_f32_32x32x16_bf16 v[64:79], v[144:147], v[160:163], v[64:79]
	v_mfma_f32_32x32x16_bf16 v[0:15], v[144:147], v[236:239], v[0:15]
	s_waitcnt lgkmcnt(4)
	v_mfma_f32_32x32x16_bf16 v[80:95], v[132:135], v[164:167], v[80:95]
	v_mfma_f32_32x32x16_bf16 v[16:31], v[132:135], v[240:243], v[16:31]
	v_mfma_f32_32x32x16_bf16 v[64:79], v[148:151], v[164:167], v[64:79]
	v_mfma_f32_32x32x16_bf16 v[0:15], v[148:151], v[240:243], v[0:15]
	s_waitcnt lgkmcnt(2)
	v_mfma_f32_32x32x16_bf16 v[80:95], v[136:139], v[168:171], v[80:95]
	v_mfma_f32_32x32x16_bf16 v[16:31], v[136:139], v[244:247], v[16:31]
	v_mfma_f32_32x32x16_bf16 v[64:79], v[152:155], v[168:171], v[64:79]
	v_mfma_f32_32x32x16_bf16 v[0:15], v[152:155], v[244:247], v[0:15]
	s_waitcnt lgkmcnt(0)
	v_mfma_f32_32x32x16_bf16 v[80:95], v[140:143], v[172:175], v[80:95]
	v_mfma_f32_32x32x16_bf16 v[16:31], v[140:143], v[248:251], v[16:31]
	v_mfma_f32_32x32x16_bf16 v[64:79], v[156:159], v[172:175], v[64:79]
	v_mfma_f32_32x32x16_bf16 v[0:15], v[156:159], v[248:251], v[0:15]
	s_add_i32 s12, s12, 1
	s_cmp_lg_u32 s12, 8
	s_cbranch_scc1 .Lga_loop
	s_nop 15
	s_setprio 0
	s_barrier
	s_add_u32 s2, s27, 0x4a40000
	s_addc_u32 s3, s28, 0
	s_lshl_b64 s[0:1], s[0:1], 1
	s_add_u32 s0, s27, s0
	s_addc_u32 s1, s28, s1
	s_add_u32 s0, s0, 0x4a50000
	s_addc_u32 s1, s1, 0
	v_and_b32_e32 v128, 0x7fffff80, v181
	v_and_or_b32 v129, v185, 4, v128
	v_or_b32_e32 v128, s80, v183
	v_lshlrev_b32_e32 v132, 2, v128
	v_mov_b32_e32 v128, v252
	s_waitcnt vmcnt(0)
	s_nop 2
	v_mul_f32_e64 v112, v112, v128
	v_mul_f32_e64 v113, v113, v128
	v_cvt_pk_bf16_f32 v130, v112, v113
	v_mul_f32_e64 v112, v114, v128
	v_mul_f32_e64 v113, v115, v128
	v_mul_f32_e64 v96, v96, v128
	v_mul_f32_e64 v97, v97, v128
	v_cvt_pk_bf16_f32 v131, v112, v113
	v_lshlrev_b32_e32 v112, 1, v129
	v_mad_u32_u24 v112, v183, s73, v112
	v_pk_mul_f32 v[98:99], v[98:99], v[128:129] op_sel_hi:[1,0]
	s_nop 2
	v_pk_mul_f32 v[64:65], v[64:65], v[128:129] op_sel_hi:[1,0]
	v_pk_mul_f32 v[66:67], v[66:67], v[128:129] op_sel_hi:[1,0]
	v_cvt_pk_bf16_f32 v64, v64, v65
	v_cvt_pk_bf16_f32 v65, v66, v67
	v_pk_mul_f32 v[66:67], v[68:69], v[128:129] op_sel_hi:[1,0]
	v_pk_mul_f32 v[68:69], v[70:71], v[128:129] op_sel_hi:[1,0]
	v_cvt_pk_bf16_f32 v66, v66, v67
	v_cvt_pk_bf16_f32 v67, v68, v69
	ds_write2_b64 v112, v[64:65], v[66:67] offset0:24 offset1:26
	v_pk_mul_f32 v[64:65], v[72:73], v[128:129] op_sel_hi:[1,0]
	v_pk_mul_f32 v[66:67], v[74:75], v[128:129] op_sel_hi:[1,0]
	v_cvt_pk_bf16_f32 v64, v64, v65
	v_cvt_pk_bf16_f32 v65, v66, v67
	v_pk_mul_f32 v[66:67], v[76:77], v[128:129] op_sel_hi:[1,0]
	v_pk_mul_f32 v[68:69], v[78:79], v[128:129] op_sel_hi:[1,0]
	v_cvt_pk_bf16_f32 v66, v66, v67
	v_cvt_pk_bf16_f32 v67, v68, v69
	ds_write2_b64 v112, v[64:65], v[66:67] offset0:28 offset1:30
	v_or_b32_e32 v64, 0x80, v132
	v_mov_b32_e32 v64, v253
	v_mul_f32_e64 v114, v116, v128
	v_mul_f32_e64 v115, v117, v128
	v_mul_f32_e64 v116, v118, v128
	v_mul_f32_e64 v117, v119, v128
	v_cvt_pk_bf16_f32 v96, v96, v97
	v_cvt_pk_bf16_f32 v97, v98, v99
	v_pk_mul_f32 v[98:99], v[100:101], v[128:129] op_sel_hi:[1,0]
	v_pk_mul_f32 v[100:101], v[102:103], v[128:129] op_sel_hi:[1,0]
	v_cvt_pk_bf16_f32 v114, v114, v115
	s_nop 1
	v_mul_f32_e64 v80, v80, v128
	v_mul_f32_e64 v81, v81, v128
	v_mul_f32_e64 v82, v82, v128
	v_mul_f32_e64 v83, v83, v128
	v_cvt_pk_bf16_f32 v80, v80, v81
	v_cvt_pk_bf16_f32 v81, v82, v83
	v_pk_mul_f32 v[82:83], v[84:85], v[128:129] op_sel_hi:[1,0]
	v_pk_mul_f32 v[84:85], v[86:87], v[128:129] op_sel_hi:[1,0]
	v_cvt_pk_bf16_f32 v115, v116, v117
	v_cvt_pk_bf16_f32 v98, v98, v99
	v_cvt_pk_bf16_f32 v99, v100, v101
	v_cvt_pk_bf16_f32 v82, v82, v83
	v_cvt_pk_bf16_f32 v83, v84, v85
	ds_write2_b64 v112, v[130:131], v[114:115] offset1:2
	v_pk_mul_f32 v[114:115], v[120:121], v[128:129] op_sel_hi:[1,0]
	v_pk_mul_f32 v[116:117], v[122:123], v[128:129] op_sel_hi:[1,0]
	ds_write2_b64 v112, v[96:97], v[98:99] offset0:8 offset1:10
	v_pk_mul_f32 v[96:97], v[104:105], v[128:129] op_sel_hi:[1,0]
	v_pk_mul_f32 v[98:99], v[106:107], v[128:129] op_sel_hi:[1,0]
	ds_write2_b64 v112, v[80:81], v[82:83] offset0:16 offset1:18
	v_pk_mul_f32 v[80:81], v[88:89], v[128:129] op_sel_hi:[1,0]
	v_pk_mul_f32 v[82:83], v[90:91], v[128:129] op_sel_hi:[1,0]
	v_cvt_pk_bf16_f32 v114, v114, v115
	v_cvt_pk_bf16_f32 v115, v116, v117
	v_pk_mul_f32 v[116:117], v[124:125], v[128:129] op_sel_hi:[1,0]
	v_pk_mul_f32 v[118:119], v[126:127], v[128:129] op_sel_hi:[1,0]
	v_cvt_pk_bf16_f32 v96, v96, v97
	v_cvt_pk_bf16_f32 v97, v98, v99
	v_pk_mul_f32 v[98:99], v[108:109], v[128:129] op_sel_hi:[1,0]
	v_pk_mul_f32 v[100:101], v[110:111], v[128:129] op_sel_hi:[1,0]
	v_cvt_pk_bf16_f32 v80, v80, v81
	v_cvt_pk_bf16_f32 v81, v82, v83
	v_pk_mul_f32 v[82:83], v[92:93], v[128:129] op_sel_hi:[1,0]
	v_pk_mul_f32 v[84:85], v[94:95], v[128:129] op_sel_hi:[1,0]
	v_cvt_pk_bf16_f32 v116, v116, v117
	v_cvt_pk_bf16_f32 v117, v118, v119
	v_cvt_pk_bf16_f32 v98, v98, v99
	v_cvt_pk_bf16_f32 v99, v100, v101
	v_cvt_pk_bf16_f32 v82, v82, v83
	v_cvt_pk_bf16_f32 v83, v84, v85
	s_mov_b32 s2, 0
	ds_write2_b64 v112, v[114:115], v[116:117] offset0:4 offset1:6
	ds_write2_b64 v112, v[96:97], v[98:99] offset0:12 offset1:14
	ds_write2_b64 v112, v[80:81], v[82:83] offset0:20 offset1:22
	s_waitcnt vmcnt(0)
; template <int NTW>
; DI void inproj_tile(const Params& p, int l, int mt, int ntile, char* lds) {
;     ...
;   for (int im = 0; im < 2; ++im) {
;     const int tl = wm * 64 + im * 32 + l31;
;     const float r = rn[(size_t)mt * 128 + tl];
; #pragma unroll
;     for (int in = 0; in < NTW; ++in)
; #pragma unroll
;       for (int g = 0; g < 4; ++g) {
;         const int n = wn * 32 * NTW + in * 32 + 8 * g + 4 * hi;
;         u32x2 o; o[0] = pk2(acc[in][im][4 * g] * r, acc[in][im][4 * g + 1] * r); o[1] = pk2(acc[in][im][4 * g + 2] * r, acc[in][im][4 * g + 3] * r);
;         *(u32x2*)(lds + tl * RS + n * 2) = o;
;       }
;   }
;   __syncthreads();
	v_pk_mul_f32 v[48:49], v[48:49], v[64:65] op_sel_hi:[1,0]
	v_pk_mul_f32 v[50:51], v[50:51], v[64:65] op_sel_hi:[1,0]
	v_pk_mul_f32 v[32:33], v[32:33], v[64:65] op_sel_hi:[1,0]
	v_pk_mul_f32 v[34:35], v[34:35], v[64:65] op_sel_hi:[1,0]
	v_pk_mul_f32 v[16:17], v[16:17], v[64:65] op_sel_hi:[1,0]
	v_pk_mul_f32 v[18:19], v[18:19], v[64:65] op_sel_hi:[1,0]
	v_pk_mul_f32 v[0:1], v[0:1], v[64:65] op_sel_hi:[1,0]
	v_pk_mul_f32 v[2:3], v[2:3], v[64:65] op_sel_hi:[1,0]
	v_cvt_pk_bf16_f32 v48, v48, v49
	v_cvt_pk_bf16_f32 v49, v50, v51
	v_pk_mul_f32 v[50:51], v[52:53], v[64:65] op_sel_hi:[1,0]
	v_pk_mul_f32 v[52:53], v[54:55], v[64:65] op_sel_hi:[1,0]
	v_cvt_pk_bf16_f32 v32, v32, v33
	v_cvt_pk_bf16_f32 v33, v34, v35
	v_pk_mul_f32 v[34:35], v[36:37], v[64:65] op_sel_hi:[1,0]
	v_pk_mul_f32 v[36:37], v[38:39], v[64:65] op_sel_hi:[1,0]
	v_cvt_pk_bf16_f32 v16, v16, v17
	v_cvt_pk_bf16_f32 v17, v18, v19
	v_pk_mul_f32 v[18:19], v[20:21], v[64:65] op_sel_hi:[1,0]
	v_pk_mul_f32 v[20:21], v[22:23], v[64:65] op_sel_hi:[1,0]
	v_cvt_pk_bf16_f32 v0, v0, v1
	v_cvt_pk_bf16_f32 v1, v2, v3
	v_pk_mul_f32 v[2:3], v[4:5], v[64:65] op_sel_hi:[1,0]
	v_pk_mul_f32 v[4:5], v[6:7], v[64:65] op_sel_hi:[1,0]
	v_cvt_pk_bf16_f32 v50, v50, v51
	v_cvt_pk_bf16_f32 v51, v52, v53
	v_add_u32_e32 v54, 0x4000, v112
	v_cvt_pk_bf16_f32 v34, v34, v35
	v_cvt_pk_bf16_f32 v35, v36, v37
	v_cvt_pk_bf16_f32 v18, v18, v19
	v_cvt_pk_bf16_f32 v19, v20, v21
	v_cvt_pk_bf16_f32 v2, v2, v3
	v_cvt_pk_bf16_f32 v3, v4, v5
	ds_write2_b64 v54, v[48:49], v[50:51] offset0:64 offset1:66
	v_pk_mul_f32 v[48:49], v[56:57], v[64:65] op_sel_hi:[1,0]
	v_pk_mul_f32 v[50:51], v[58:59], v[64:65] op_sel_hi:[1,0]
	ds_write2_b64 v54, v[32:33], v[34:35] offset0:72 offset1:74
	v_pk_mul_f32 v[32:33], v[40:41], v[64:65] op_sel_hi:[1,0]
	v_pk_mul_f32 v[34:35], v[42:43], v[64:65] op_sel_hi:[1,0]
	ds_write2_b64 v54, v[16:17], v[18:19] offset0:80 offset1:82
	v_pk_mul_f32 v[16:17], v[24:25], v[64:65] op_sel_hi:[1,0]
	v_pk_mul_f32 v[18:19], v[26:27], v[64:65] op_sel_hi:[1,0]
	ds_write2_b64 v54, v[0:1], v[2:3] offset0:88 offset1:90
	v_pk_mul_f32 v[0:1], v[8:9], v[64:65] op_sel_hi:[1,0]
	v_pk_mul_f32 v[2:3], v[10:11], v[64:65] op_sel_hi:[1,0]
	v_cvt_pk_bf16_f32 v48, v48, v49
	v_cvt_pk_bf16_f32 v49, v50, v51
	v_pk_mul_f32 v[50:51], v[60:61], v[64:65] op_sel_hi:[1,0]
	v_pk_mul_f32 v[52:53], v[62:63], v[64:65] op_sel_hi:[1,0]
	v_cvt_pk_bf16_f32 v32, v32, v33
	v_cvt_pk_bf16_f32 v33, v34, v35
	v_pk_mul_f32 v[34:35], v[44:45], v[64:65] op_sel_hi:[1,0]
	v_pk_mul_f32 v[36:37], v[46:47], v[64:65] op_sel_hi:[1,0]
	v_cvt_pk_bf16_f32 v16, v16, v17
	v_cvt_pk_bf16_f32 v17, v18, v19
	v_pk_mul_f32 v[18:19], v[28:29], v[64:65] op_sel_hi:[1,0]
	v_pk_mul_f32 v[20:21], v[30:31], v[64:65] op_sel_hi:[1,0]
	v_cvt_pk_bf16_f32 v0, v0, v1
	v_cvt_pk_bf16_f32 v1, v2, v3
	v_pk_mul_f32 v[2:3], v[12:13], v[64:65] op_sel_hi:[1,0]
	v_pk_mul_f32 v[4:5], v[14:15], v[64:65] op_sel_hi:[1,0]
	v_cvt_pk_bf16_f32 v50, v50, v51
	v_cvt_pk_bf16_f32 v51, v52, v53
	v_cvt_pk_bf16_f32 v34, v34, v35
	v_cvt_pk_bf16_f32 v35, v36, v37
	v_cvt_pk_bf16_f32 v18, v18, v19
	v_cvt_pk_bf16_f32 v19, v20, v21
	v_cvt_pk_bf16_f32 v2, v2, v3
	v_cvt_pk_bf16_f32 v3, v4, v5
	ds_write2_b64 v54, v[48:49], v[50:51] offset0:68 offset1:70
	ds_write2_b64 v54, v[32:33], v[34:35] offset0:76 offset1:78
	ds_write2_b64 v54, v[16:17], v[18:19] offset0:84 offset1:86
	ds_write2_b64 v54, v[0:1], v[2:3] offset0:92 offset1:94
	s_waitcnt lgkmcnt(0)
	s_barrier

; DI char* opq(char* q) { size_t z = 0; asm volatile("" : "+s"(z)); return q + z; }
; DI int tidx() { int t = threadIdx.x; asm volatile("" : "+v"(t)); return t; }
; #define GLOAD(dst, kt_) _Pragma("unroll") for (int i = 0; i < NCH; ++i) { dst[i] = (i < NCHW) ? ldw(i, tid >> 3, (kt_) * 64 + (tid & 7) * 8) : ldx(i - NCHW, tid >> 3, (kt_) * 64 + (tid & 7) * 8); }
; #define LSTORE(src, base) _Pragma("unroll") for (int i = 0; i < NCH; ++i) { const int c = tid + 256 * i; *(u32x4*)((base) + (c >> 3) * 144 + (c & 7) * 16) = src[i]; }
; template <int WGN, int INS, int IMS, bool DB, class LdW, class LdX>
; DI void gemm_core(f32x16 (&acc)[INS][IMS], const int KT, LdW ldw, LdX ldx, char* lds, const int tid) {
;   constexpr int WGM = 4 / WGN;
;   constexpr int WROWS = WGN * 32 * INS, XROWS = WGM * 32 * IMS, NROWS = WROWS + XROWS, NCH = NROWS / 32, NCHW = WROWS / 32, BUFB = NROWS * 144;
;   const int lane = tid & 63, wid = tid >> 6, l31 = lane & 31, hi = lane >> 5;
;   const int wn = (WGN == 2) ? (wid >> 1) : wid, wm = (WGN == 2) ? (wid & 1) : 0;
;   const int offa = (wn * 32 * INS + l31) * 144 + hi * 16;
;   const int offb = (WROWS + wm * 32 * IMS + l31) * 144 + hi * 16;
; #pragma unroll
;   for (int a = 0; a < INS; ++a)
; #pragma unroll
;     for (int b = 0; b < IMS; ++b)
; #pragma unroll
;       for (int r = 0; r < 16; ++r) acc[a][b][r] = 0.f;
;     ...
;   if (DB) {
;     u32x4 preA[NCH], preB[NCH];
;     GLOAD(preA, 0)
;     GLOAD(preB, 1)
;     __syncthreads();
;     LSTORE(preA, lds)
;     __syncthreads();
; DI void outproj_item(const Params& p, int l, int it, char* lds) {
;   char* const ws_ = opq(p.ws);
;   const int mt = (it & 7) * 16 + ((it >> 3) & 15), nt = it >> 7;
;   const u16* W = (const u16*)(ws_ + OFF_WOUT) + ((size_t)l * 1024 + nt * 256) * 1024;
;   const u16* Y = (const u16*)(ws_ + OFF_XB) + (size_t)mt * 128 * 1024;
;   f32x16 acc[4][2];
;   const int tid = tidx();
;   gemm_core<2, 4, 2, false>(acc, 16, [&](int i, int r0, int k) -> u32x4 { return *(const u32x4*)((W + i * 32768) + (unsigned)(r0 * 1024 + k)); },
;                [&](int i, int r0, int k) -> u32x4 { return *(const u32x4*)((Y + i * 32768) + (unsigned)(r0 * 1024 + k)); }, lds, tid);
.LBB0_533:
	s_mov_b64 s[0:1], 0
	s_add_u32 s28, s90, s0
	s_addc_u32 s29, s91, s1
	s_lshl_b32 s0, s27, 4
	s_and_b32 s0, s0, 0x70
	s_bfe_u32 s1, s27, 0x40003
	s_ashr_i32 s30, s27, 7
	s_or_b32 s4, s0, s1
	s_lshl_b32 s0, s30, 8
	s_ashr_i32 s1, s0, 31
	s_add_u32 s5, s28, s26
	s_addc_u32 s6, s29, 0
	s_lshl_b64 s[2:3], s[0:1], 11
	s_add_u32 s18, s5, s2
	s_addc_u32 s19, s6, s3
	s_add_u32 s2, s18, 0x1a00000
	s_addc_u32 s3, s19, 0
	s_lshl_b32 s80, s4, 7
	s_lshl_b32 s4, s4, 18
	s_add_u32 s24, s28, s4
	s_addc_u32 s25, s29, 0
	s_add_u32 s4, s24, 0x2a40000
	s_addc_u32 s5, s25, 0
	v_mov_b32_e32 v181, v176
	v_and_b32_e32 v183, 0x5f, v181
	v_lshlrev_b32_e32 v185, 4, v181
	v_and_b32_e32 v220, 63, v181
	v_lshrrev_b32_e32 v221, 6, v181
	v_lshrrev_b32_e32 v222, 3, v220
	v_readfirstlane_b32 s13, v221
	v_and_b32_e32 v223, 7, v220
	v_bfe_u32 v224, v220, 4, 2
	v_xor_b32_e32 v223, v223, v224
	v_lshlrev_b32_e32 v223, 4, v223
	v_and_b32_e32 v224, 1, v221
	v_lshrrev_b32_e32 v225, 1, v221
	v_lshlrev_b32_e32 v224, 5, v224
	v_lshl_add_u32 v224, v225, 7, v224
	v_add_u32_e32 v224, v224, v222
	v_lshl_add_u32 v225, v221, 5, v222
	v_lshl_or_b32 v210, v224, 11, v223
	v_lshl_or_b32 v216, v225, 11, v223
	v_xor_b32_e32 v224, 64, v210
	v_xor_b32_e32 v225, 64, v216
	v_add_u32_e32 v211, 0x3c00, v224
	v_add_u32_e32 v217, 0x3c00, v225
	v_add_u32_e32 v212, 0x7800, v210
	v_add_u32_e32 v218, 0x7800, v216
	v_add_u32_e32 v213, 0xb400, v224
	v_add_u32_e32 v219, 0xb400, v225
	v_and_b32_e32 v222, 31, v220
	v_lshrrev_b32_e32 v223, 5, v220
	v_bfe_u32 v224, v220, 1, 3
	v_xor_b32_e32 v223, v223, v224
	v_lshlrev_b32_e32 v223, 4, v223
	v_lshrrev_b32_e32 v224, 1, v221
	v_and_b32_e32 v225, 1, v221
	v_lshl_add_u32 v224, v224, 6, v222
	v_lshl_add_u32 v225, v225, 6, v222
	v_lshl_or_b32 v202, v224, 7, v223
	v_lshl_or_b32 v206, v225, 7, v223
	v_xor_b32_e32 v203, 32, v202
	v_xor_b32_e32 v207, 32, v206
	v_xor_b32_e32 v204, 64, v202
	v_xor_b32_e32 v208, 64, v206
	v_xor_b32_e32 v205, 96, v202
	v_xor_b32_e32 v209, 96, v206
	s_lshl_b32 s13, s13, 12
	s_sub_u32 s10, s4, 0x80
	s_subb_u32 s11, s5, 0
	s_add_u32 s8, s2, 0x1ff80
	s_addc_u32 s9, s3, 0
	s_sub_u32 s6, s2, 0x80
	s_subb_u32 s7, s3, 0
	s_mov_b32 s12, 0
	s_setprio 1
	s_waitcnt lgkmcnt(0)
	s_barrier
	s_add_u32 s10, s10, 0x80
	s_addc_u32 s11, s11, 0
	s_add_u32 m0, s13, 0
	s_nop 0
	global_load_lds_dwordx4 v216, s[10:11] sc1
	global_load_lds_dwordx4 v217, s[10:11] offset:1024 sc1
	global_load_lds_dwordx4 v218, s[10:11] offset:2048 sc1
	global_load_lds_dwordx4 v219, s[10:11] offset:3072 sc1
	s_add_u32 s6, s6, 0x80
	s_addc_u32 s7, s7, 0
	s_add_u32 m0, s13, 32768
	s_nop 0
	global_load_lds_dwordx4 v210, s[6:7]
	global_load_lds_dwordx4 v211, s[6:7] offset:1024
	global_load_lds_dwordx4 v212, s[6:7] offset:2048
	global_load_lds_dwordx4 v213, s[6:7] offset:3072
	v_mov_b32_e32 v112, 0
	v_mov_b32_e32 v113, 0
	v_mov_b32_e32 v114, 0
	v_mov_b32_e32 v115, 0
	v_mov_b32_e32 v116, 0
	v_mov_b32_e32 v117, 0
	v_mov_b32_e32 v118, 0
	v_mov_b32_e32 v119, 0
	v_mov_b32_e32 v120, 0
	v_mov_b32_e32 v121, 0
	v_mov_b32_e32 v122, 0
	v_mov_b32_e32 v123, 0
	v_mov_b32_e32 v124, 0
	v_mov_b32_e32 v125, 0
	v_mov_b32_e32 v126, 0
	v_mov_b32_e32 v127, 0
	v_mov_b32_e32 v64, 0
	v_mov_b32_e32 v65, 0
	v_mov_b32_e32 v66, 0
	v_mov_b32_e32 v67, 0
	v_mov_b32_e32 v68, 0
	v_mov_b32_e32 v69, 0
	v_mov_b32_e32 v70, 0
	v_mov_b32_e32 v71, 0
	v_mov_b32_e32 v72, 0
	v_mov_b32_e32 v73, 0
	v_mov_b32_e32 v74, 0
	v_mov_b32_e32 v75, 0
	v_mov_b32_e32 v76, 0
	v_mov_b32_e32 v77, 0
	v_mov_b32_e32 v78, 0
	v_mov_b32_e32 v79, 0
	v_mov_b32_e32 v96, 0
	v_mov_b32_e32 v97, 0
	v_mov_b32_e32 v98, 0
	v_mov_b32_e32 v99, 0
	v_mov_b32_e32 v100, 0
	v_mov_b32_e32 v101, 0
	v_mov_b32_e32 v102, 0
	v_mov_b32_e32 v103, 0
	v_mov_b32_e32 v104, 0
	v_mov_b32_e32 v105, 0
	v_mov_b32_e32 v106, 0
	v_mov_b32_e32 v107, 0
	v_mov_b32_e32 v108, 0
	v_mov_b32_e32 v109, 0
	v_mov_b32_e32 v110, 0
	v_mov_b32_e32 v111, 0
	v_mov_b32_e32 v32, 0
	v_mov_b32_e32 v33, 0
	v_mov_b32_e32 v34, 0
	v_mov_b32_e32 v35, 0
	v_mov_b32_e32 v36, 0
	v_mov_b32_e32 v37, 0
	v_mov_b32_e32 v38, 0
	v_mov_b32_e32 v39, 0
	v_mov_b32_e32 v40, 0
	v_mov_b32_e32 v41, 0
	v_mov_b32_e32 v42, 0
	v_mov_b32_e32 v43, 0
	v_mov_b32_e32 v44, 0
	v_mov_b32_e32 v45, 0
	v_mov_b32_e32 v46, 0
	v_mov_b32_e32 v47, 0
	v_mov_b32_e32 v80, 0
	v_mov_b32_e32 v81, 0
	v_mov_b32_e32 v82, 0
	v_mov_b32_e32 v83, 0
	v_mov_b32_e32 v84, 0
	v_mov_b32_e32 v85, 0
	v_mov_b32_e32 v86, 0
	v_mov_b32_e32 v87, 0
	v_mov_b32_e32 v88, 0
	v_mov_b32_e32 v89, 0
	v_mov_b32_e32 v90, 0
	v_mov_b32_e32 v91, 0
	v_mov_b32_e32 v92, 0
	v_mov_b32_e32 v93, 0
	v_mov_b32_e32 v94, 0
	v_mov_b32_e32 v95, 0
	v_mov_b32_e32 v16, 0
	v_mov_b32_e32 v17, 0
	v_mov_b32_e32 v18, 0
	v_mov_b32_e32 v19, 0
	v_mov_b32_e32 v20, 0
	v_mov_b32_e32 v21, 0
	v_mov_b32_e32 v22, 0
	v_mov_b32_e32 v23, 0
	v_mov_b32_e32 v24, 0
	v_mov_b32_e32 v25, 0
	v_mov_b32_e32 v26, 0
	v_mov_b32_e32 v27, 0
	v_mov_b32_e32 v28, 0
	v_mov_b32_e32 v29, 0
	v_mov_b32_e32 v30, 0
	v_mov_b32_e32 v31, 0
	v_mov_b32_e32 v48, 0
	v_mov_b32_e32 v49, 0
	v_mov_b32_e32 v50, 0
	v_mov_b32_e32 v51, 0
	v_mov_b32_e32 v52, 0
	v_mov_b32_e32 v53, 0
	v_mov_b32_e32 v54, 0
	v_mov_b32_e32 v55, 0
	v_mov_b32_e32 v56, 0
	v_mov_b32_e32 v57, 0
	v_mov_b32_e32 v58, 0
	v_mov_b32_e32 v59, 0
	v_mov_b32_e32 v60, 0
	v_mov_b32_e32 v61, 0
	v_mov_b32_e32 v62, 0
	v_mov_b32_e32 v63, 0
	v_mov_b32_e32 v0, 0
	v_mov_b32_e32 v1, 0
	v_mov_b32_e32 v2, 0
	v_mov_b32_e32 v3, 0
	v_mov_b32_e32 v4, 0
	v_mov_b32_e32 v5, 0
	v_mov_b32_e32 v6, 0
	v_mov_b32_e32 v7, 0
	v_mov_b32_e32 v8, 0
	v_mov_b32_e32 v9, 0
	v_mov_b32_e32 v10, 0
	v_mov_b32_e32 v11, 0
	v_mov_b32_e32 v12, 0
	v_mov_b32_e32 v13, 0
	v_mov_b32_e32 v14, 0
	v_mov_b32_e32 v15, 0

; DI void outproj_item(const Params& p, int l, int it, char* lds) {
;     ...
;   const int lane = tid & 63, wid = tid >> 6, l31 = lane & 31, hi = lane >> 5, wn = wid >> 1, wm = wid & 1;
;   u16* outb = (u16*)(ws_ + OFF_OUTB);
;   float* ssq = (float*)(ws_ + OFF_SSQ);
;   constexpr int RS = 256 * 2 + 16;
;   __syncthreads();
; #pragma unroll
;   for (int im = 0; im < 2; ++im) {
;     const int tl = wm * 64 + im * 32 + l31;
;     float ss = 0.f;
; #pragma unroll
;     for (int in = 0; in < 4; ++in)
; #pragma unroll
;       for (int g = 0; g < 4; ++g) {
;         const int n = wn * 128 + in * 32 + 8 * g + 4 * hi;
;         const float o0 = acc[in][im][4 * g], o1 = acc[in][im][4 * g + 1], o2 = acc[in][im][4 * g + 2], o3 = acc[in][im][4 * g + 3];
;         ss += o0 * o0 + o1 * o1 + o2 * o2 + o3 * o3;
;         u32x2 v; v[0] = pk2(o0, o1); v[1] = pk2(o2, o3);
;         *(u32x2*)(lds + tl * RS + n * 2) = v;
;       }
;     ss += __shfl_xor(ss, 32, 64);
;     if (hi == 0) ssq[((size_t)mt * 128 + tl) * 16 + nt * 2 + wn] = ss;
;   }
.Lgd_p1c:
	s_waitcnt lgkmcnt(6)
	v_mfma_f32_32x32x16_bf16 v[80:95], v[128:131], v[160:163], v[80:95]
	v_mfma_f32_32x32x16_bf16 v[16:31], v[128:131], v[236:239], v[16:31]
	v_mfma_f32_32x32x16_bf16 v[48:63], v[144:147], v[160:163], v[48:63]
	v_mfma_f32_32x32x16_bf16 v[0:15], v[144:147], v[236:239], v[0:15]
	s_waitcnt lgkmcnt(4)
	v_mfma_f32_32x32x16_bf16 v[80:95], v[132:135], v[164:167], v[80:95]
	v_mfma_f32_32x32x16_bf16 v[16:31], v[132:135], v[240:243], v[16:31]
	v_mfma_f32_32x32x16_bf16 v[48:63], v[148:151], v[164:167], v[48:63]
	v_mfma_f32_32x32x16_bf16 v[0:15], v[148:151], v[240:243], v[0:15]
	s_waitcnt lgkmcnt(2)
	v_mfma_f32_32x32x16_bf16 v[80:95], v[136:139], v[168:171], v[80:95]
	v_mfma_f32_32x32x16_bf16 v[16:31], v[136:139], v[244:247], v[16:31]
	v_mfma_f32_32x32x16_bf16 v[48:63], v[152:155], v[168:171], v[48:63]
	v_mfma_f32_32x32x16_bf16 v[0:15], v[152:155], v[244:247], v[0:15]
	s_waitcnt lgkmcnt(0)
	v_mfma_f32_32x32x16_bf16 v[80:95], v[140:143], v[172:175], v[80:95]
	v_mfma_f32_32x32x16_bf16 v[16:31], v[140:143], v[248:251], v[16:31]
	v_mfma_f32_32x32x16_bf16 v[48:63], v[156:159], v[172:175], v[48:63]
	v_mfma_f32_32x32x16_bf16 v[0:15], v[156:159], v[248:251], v[0:15]
	s_add_i32 s12, s12, 1
	s_cmp_lg_u32 s12, 8
	s_cbranch_scc1 .Lgd_loop
	s_nop 15
	s_setprio 0
	s_barrier
	s_lshl_b32 s2, s30, 1
	s_ashr_i32 s3, s2, 31
	s_lshl_b64 s[2:3], s[2:3], 2
	s_add_u32 s2, s28, s2
	s_addc_u32 s3, s29, s3
	s_barrier
	s_nop 9
	v_mul_f32_e32 v133, v113, v113
	v_fmac_f32_e32 v133, v112, v112
	v_fmac_f32_e32 v133, v114, v114
	v_cvt_pk_bf16_f32 v112, v112, v113
	v_cvt_pk_bf16_f32 v113, v114, v115
	v_mul_f32_e32 v114, v117, v117
	v_fmac_f32_e32 v114, v116, v116
	v_lshlrev_b32_e32 v130, 1, v181
	v_bfe_u32 v129, v181, 5, 1
	v_and_b32_e32 v130, 0xffffff00, v130
	v_and_b32_e32 v132, 64, v195
	v_fmac_f32_e32 v114, v118, v118
	v_lshl_or_b32 v131, v129, 3, v130
	v_xor_b32_e32 v130, 32, v195
	v_add_u32_e32 v132, 64, v132
	v_fmac_f32_e32 v133, v115, v115
	v_fmac_f32_e32 v114, v119, v119
	v_cmp_lt_i32_e32 vcc, v130, v132
	v_mad_u32_u24 v132, v183, s73, v131
	v_add_f32_e32 v133, v133, v114
	v_cvt_pk_bf16_f32 v114, v116, v117
	v_cvt_pk_bf16_f32 v115, v118, v119
	ds_write2_b64 v132, v[112:113], v[114:115] offset1:2
	v_mul_f32_e32 v112, v121, v121
	v_fmac_f32_e32 v112, v120, v120
	v_mul_f32_e32 v115, v125, v125
	v_fmac_f32_e32 v112, v122, v122
	v_fmac_f32_e32 v115, v124, v124
	v_fmac_f32_e32 v112, v123, v123
	v_fmac_f32_e32 v115, v126, v126
	v_add_f32_e32 v114, v112, v133
	v_fmac_f32_e32 v115, v127, v127
	v_cvt_pk_bf16_f32 v112, v120, v121
	v_cvt_pk_bf16_f32 v113, v122, v123
	v_add_f32_e32 v116, v115, v114
	v_cvt_pk_bf16_f32 v114, v124, v125
	v_cvt_pk_bf16_f32 v115, v126, v127
	ds_write2_b64 v132, v[112:113], v[114:115] offset0:4 offset1:6
	v_mul_f32_e32 v112, v97, v97
	v_fmac_f32_e32 v112, v96, v96
	v_fmac_f32_e32 v112, v98, v98
	v_cvt_pk_bf16_f32 v96, v96, v97
	v_cvt_pk_bf16_f32 v97, v98, v99
	v_mul_f32_e32 v98, v101, v101
	v_fmac_f32_e32 v98, v100, v100
	v_fmac_f32_e32 v112, v99, v99
	v_fmac_f32_e32 v98, v102, v102
	v_add_f32_e32 v112, v112, v116
	v_fmac_f32_e32 v98, v103, v103
	v_add_f32_e32 v112, v98, v112
	v_cvt_pk_bf16_f32 v98, v100, v101
	v_cvt_pk_bf16_f32 v99, v102, v103
	ds_write2_b64 v132, v[96:97], v[98:99] offset0:8 offset1:10
	v_mul_f32_e32 v96, v105, v105
	v_fmac_f32_e32 v96, v104, v104
	v_mul_f32_e32 v99, v109, v109
	v_fmac_f32_e32 v96, v106, v106
	v_fmac_f32_e32 v99, v108, v108
	v_fmac_f32_e32 v96, v107, v107
	v_fmac_f32_e32 v99, v110, v110
	v_add_f32_e32 v98, v96, v112
	v_fmac_f32_e32 v99, v111, v111
	v_cvt_pk_bf16_f32 v96, v104, v105
	v_cvt_pk_bf16_f32 v97, v106, v107
	v_add_f32_e32 v100, v99, v98
	v_cvt_pk_bf16_f32 v98, v108, v109
	v_cvt_pk_bf16_f32 v99, v110, v111
	ds_write2_b64 v132, v[96:97], v[98:99] offset0:12 offset1:14
	v_mul_f32_e32 v96, v81, v81
	v_fmac_f32_e32 v96, v80, v80
	v_fmac_f32_e32 v96, v82, v82
	v_cvt_pk_bf16_f32 v80, v80, v81
	v_cvt_pk_bf16_f32 v81, v82, v83
	v_mul_f32_e32 v82, v85, v85
	v_fmac_f32_e32 v82, v84, v84
	v_fmac_f32_e32 v96, v83, v83
	v_fmac_f32_e32 v82, v86, v86
	v_add_f32_e32 v96, v96, v100
	v_fmac_f32_e32 v82, v87, v87
	v_add_f32_e32 v96, v82, v96
	v_cvt_pk_bf16_f32 v82, v84, v85
	v_cvt_pk_bf16_f32 v83, v86, v87
	ds_write2_b64 v132, v[80:81], v[82:83] offset0:16 offset1:18
	v_mul_f32_e32 v80, v89, v89
	v_fmac_f32_e32 v80, v88, v88
	v_mul_f32_e32 v83, v93, v93
	v_fmac_f32_e32 v80, v90, v90
	v_fmac_f32_e32 v83, v92, v92
	v_fmac_f32_e32 v80, v91, v91
	v_fmac_f32_e32 v83, v94, v94
	v_add_f32_e32 v82, v80, v96
	v_fmac_f32_e32 v83, v95, v95
	v_cvt_pk_bf16_f32 v80, v88, v89
	v_cvt_pk_bf16_f32 v81, v90, v91
	v_add_f32_e32 v84, v83, v82
	v_cvt_pk_bf16_f32 v82, v92, v93
	v_cvt_pk_bf16_f32 v83, v94, v95
	ds_write2_b64 v132, v[80:81], v[82:83] offset0:20 offset1:22
	v_mul_f32_e32 v80, v49, v49
	v_fmac_f32_e32 v80, v48, v48
	v_fmac_f32_e32 v80, v50, v50
	v_cvt_pk_bf16_f32 v48, v48, v49
	v_cvt_pk_bf16_f32 v49, v50, v51
	v_mul_f32_e32 v50, v53, v53
	v_fmac_f32_e32 v50, v52, v52
	v_fmac_f32_e32 v80, v51, v51
	v_fmac_f32_e32 v50, v54, v54
	v_add_f32_e32 v80, v80, v84
	v_fmac_f32_e32 v50, v55, v55
	v_add_f32_e32 v80, v50, v80
	v_cvt_pk_bf16_f32 v50, v52, v53
	v_cvt_pk_bf16_f32 v51, v54, v55
	ds_write2_b64 v132, v[48:49], v[50:51] offset0:24 offset1:26
	v_mul_f32_e32 v48, v57, v57
	v_fmac_f32_e32 v48, v56, v56
	v_mul_f32_e32 v49, v61, v61
	v_fmac_f32_e32 v48, v58, v58
	v_fmac_f32_e32 v49, v60, v60
	v_fmac_f32_e32 v48, v59, v59
	v_fmac_f32_e32 v49, v62, v62
	v_cndmask_b32_e32 v130, v195, v130, vcc
	v_add_f32_e32 v48, v48, v80
	v_fmac_f32_e32 v49, v63, v63
	v_lshlrev_b32_e32 v130, 2, v130
	v_add_f32_e32 v48, v49, v48
	ds_bpermute_b32 v49, v130, v48
	v_ashrrev_i32_e32 v128, 7, v181
	v_cmp_eq_u32_e32 vcc, 0, v129
	v_ashrrev_i32_e32 v129, 31, v128
	v_lshl_add_u64 v[128:129], v[128:129], 2, s[2:3]
	s_mov_b64 s[2:3], 0xb250000
	v_lshl_add_u64 v[128:129], v[128:129], 0, s[2:3]
	v_cvt_pk_bf16_f32 v50, v56, v57
	v_cvt_pk_bf16_f32 v51, v58, v59
	v_cvt_pk_bf16_f32 v52, v60, v61
	v_cvt_pk_bf16_f32 v53, v62, v63
	ds_write2_b64 v132, v[50:51], v[52:53] offset0:28 offset1:30
	s_and_saveexec_b64 s[2:3], vcc
	s_cbranch_execz .LBB0_537
	v_or_b32_e32 v50, s80, v183
	v_lshlrev_b32_e32 v178, 6, v50
	v_lshl_add_u64 v[50:51], v[128:129], 0, v[178:179]
	s_waitcnt lgkmcnt(1)
	v_add_f32_e32 v48, v48, v49
	global_store_dword v[50:51], v48, off
